# v74 plus kv phase rebalance: workgroups 0-7 (which own a third kv unit) hand their conv item to workgroups 244-251
# baseline (speedup 1.0000x reference)
.LBB0_523:
	global_load_ushort v1, v33, s[64:65] offset:18
	s_movk_i32 s2, 0x100
	v_readlane_b32 s14, v252, 47
	v_readlane_b32 s15, v252, 48
	s_waitcnt vmcnt(0)
	v_readfirstlane_b32 s0, v1
	s_cmp_lg_u32 s0, 0
	s_cselect_b64 s[0:1], -1, 0
	s_cmp_lg_u64 s[0:1], 0
	s_waitcnt lgkmcnt(0)
	s_addc_u32 s4, s2, 0
	s_not_b32 s3, s7
	s_cmp_lg_u64 s[0:1], 0
	s_addc_u32 s5, s3, s2
	s_cmp_lt_u32 s7, 8
	s_cselect_b32 s5, 0x104, s5
	s_cmpk_lt_i32 s5, 0x104
	s_cbranch_scc0 .LBB0_535
	v_and_b32_e32 v162, 0x3f8, v0
	v_readlane_b32 s0, v253, 7
	v_lshlrev_b32_e32 v20, 2, v162
	v_readlane_b32 s1, v253, 8
	s_nop 4
	global_load_dwordx4 v[0:3], v20, s[0:1] offset:16
	global_load_dwordx4 v[4:7], v20, s[0:1]
	v_readlane_b32 s0, v253, 5
	v_readlane_b32 s1, v253, 6
	s_nop 4
	global_load_dwordx4 v[8:11], v20, s[0:1] offset:16
	global_load_dwordx4 v[12:15], v20, s[0:1]
	v_readlane_b32 s0, v253, 9
	v_readlane_b32 s1, v253, 10
	s_nop 4
	global_load_dwordx4 v[16:19], v20, s[0:1] offset:16
	s_nop 0
	global_load_dwordx4 v[20:23], v20, s[0:1]
	v_readlane_b32 s0, v252, 17
	v_ashrrev_i32_e32 v24, 3, v88
	v_lshlrev_b32_e32 v32, 1, v162
	v_readlane_b32 s1, v252, 18
	s_lshl_b32 s6, s4, 6
	v_and_b32_e32 v24, -16, v24
	v_lshl_add_u64 v[164:165], s[0:1], 0, v[32:33]
	s_add_i32 s0, s6, 0xffffffbf
	v_add_u32_e32 v24, s0, v24
	s_lshl_b32 s0, s7, 6
	v_subrev_u32_e32 v163, s0, v24
	s_sub_i32 s0, s7, 0xf4
	s_cmp_lt_u32 s0, 8
	s_cselect_b32 s4, 0xf4, s4
	s_lshl_b32 s6, s4, 6
	s_branch .LBB0_526
